# mlstm_out: the 32 inter-chunk readout loads of a thread issued together
# speedup vs baseline: 1.0129x; 1.0042x over previous
.LBB0_212:
	s_or_b64 exec, exec, s[20:21]
	s_load_dwordx2 s[6:7], s[0:1], 0x150
	s_and_b32 s22, s10, 0xffffff80
	s_lshl_b64 s[20:21], s[10:11], 10
	v_mov_b32_e32 v9, v169
	v_lshlrev_b32_e32 v4, 3, v12
	s_waitcnt lgkmcnt(0)
	s_add_u32 s6, s6, s20
	s_addc_u32 s7, s7, s21
	v_lshl_add_u64 v[0:1], s[6:7], 0, v[8:9]
	v_lshlrev_b32_e32 v6, 3, v33
	v_lshrrev_b32_e32 v7, 3, v12
	v_lshlrev_b32_e32 v9, 2, v33
	v_and_or_b32 v9, v9, 24, v7
	v_and_b32_e32 v7, 48, v4
	v_add_u32_e32 v4, s24, v6
	v_ashrrev_i32_e32 v4, 6, v4
	v_lshlrev_b32_e32 v5, 2, v12
	v_add_u32_e32 v4, s22, v4
	v_and_b32_e32 v13, 4, v5
	v_ashrrev_i32_e32 v5, 31, v4
	v_lshlrev_b64 v[4:5], 15, v[4:5]
	v_and_or_b32 v10, v6, 8, v7
	v_lshlrev_b32_e32 v168, 10, v9
	v_lshl_add_u64 v[4:5], s[18:19], 0, v[4:5]
	v_lshl_add_u64 v[4:5], v[4:5], 0, v[168:169]
	v_lshlrev_b32_e32 v168, 4, v10
	v_lshl_add_u64 v[10:11], v[4:5], 0, v[168:169]
	v_lshlrev_b32_e32 v168, 1, v13
	v_add_co_u32_e32 v0, vcc, 0x2d301000, v0
	v_lshl_add_u64 v[10:11], v[10:11], 0, v[168:169]
	s_nop 0
	v_addc_co_u32_e32 v1, vcc, 0, v1, vcc
	global_load_dwordx2 v[10:11], v[10:11], off
	v_cmp_eq_u32_e32 vcc, 0, v12
	global_load_dwordx4 v[0:3], v[0:1], off offset:2048
	s_waitcnt vmcnt(1)
	v_lshlrev_b32_e32 v9, 16, v10
	v_and_b32_e32 v10, 0xffff0000, v10
	s_waitcnt vmcnt(0)
	v_mul_f32_e32 v10, v1, v10
	v_fmac_f32_e32 v10, v0, v9
	v_lshlrev_b32_e32 v9, 16, v11
	v_fmac_f32_e32 v10, v2, v9
	v_and_b32_e32 v9, 0xffff0000, v11
	v_fmac_f32_e32 v10, v3, v9
	s_nop 1
	v_add_f32_dpp v9, v10, v10 quad_perm:[1,0,3,2] row_mask:0xf bank_mask:0xf bound_ctrl:1
	s_nop 1
	v_add_f32_dpp v9, v9, v9 quad_perm:[2,3,0,1] row_mask:0xf bank_mask:0xf bound_ctrl:1
	s_nop 1
	v_add_f32_dpp v9, v9, v9 row_half_mirror row_mask:0xf bank_mask:0xf bound_ctrl:1
	s_nop 1
	v_add_f32_dpp v9, v9, v9 row_mirror row_mask:0xf bank_mask:0xf bound_ctrl:1
	s_nop 0
	v_readlane_b32 s6, v9, 0
	v_readlane_b32 s11, v9, 16
	v_readlane_b32 s7, v9, 32
	v_readlane_b32 s20, v9, 48
	v_lshl_add_u32 v9, v6, 2, 0
	s_and_saveexec_b64 s[18:19], vcc
	v_mov_b32_e32 v10, s11
	v_mov_b32_e32 v11, s20
	v_pk_add_f32 v[10:11], s[6:7], v[10:11]
	s_nop 0
	v_add_f32_e32 v10, v10, v11
	ds_write_b32 v9, v10 offset:10496
	s_or_b64 exec, exec, s[18:19]
	v_or_b32_e32 v10, 1, v6
	v_and_or_b32 v10, v10, 9, v7
	v_lshlrev_b32_e32 v10, 4, v10
	v_mov_b32_e32 v11, v169
	v_lshl_add_u64 v[10:11], v[4:5], 0, v[10:11]
	v_lshl_add_u64 v[10:11], v[10:11], 0, v[168:169]
	global_load_dwordx2 v[10:11], v[10:11], off
	s_waitcnt vmcnt(0)
	v_lshlrev_b32_e32 v13, 16, v10
	v_and_b32_e32 v10, 0xffff0000, v10
	v_mul_f32_e32 v10, v1, v10
	v_fmac_f32_e32 v10, v0, v13
	v_lshlrev_b32_e32 v13, 16, v11
	v_fmac_f32_e32 v10, v2, v13
	v_and_b32_e32 v11, 0xffff0000, v11
	v_fmac_f32_e32 v10, v3, v11
	s_nop 1
	v_add_f32_dpp v10, v10, v10 quad_perm:[1,0,3,2] row_mask:0xf bank_mask:0xf bound_ctrl:1
	s_nop 1
	v_add_f32_dpp v10, v10, v10 quad_perm:[2,3,0,1] row_mask:0xf bank_mask:0xf bound_ctrl:1
	s_nop 1
	v_add_f32_dpp v10, v10, v10 row_half_mirror row_mask:0xf bank_mask:0xf bound_ctrl:1
	s_nop 1
	v_add_f32_dpp v10, v10, v10 row_mirror row_mask:0xf bank_mask:0xf bound_ctrl:1
	s_nop 0
	v_readlane_b32 s18, v10, 0
	v_readlane_b32 s11, v10, 16
	v_readlane_b32 s19, v10, 32
	v_readlane_b32 s20, v10, 48
	s_and_saveexec_b64 s[6:7], vcc
	v_mov_b32_e32 v10, s11
	v_mov_b32_e32 v11, s20
	v_pk_add_f32 v[10:11], s[18:19], v[10:11]
	s_nop 0
	v_add_f32_e32 v10, v10, v11
	ds_write_b32 v9, v10 offset:10500
	s_or_b64 exec, exec, s[6:7]
	v_or_b32_e32 v10, 2, v6
	v_and_or_b32 v10, v10, 10, v7
	v_lshlrev_b32_e32 v10, 4, v10
	v_mov_b32_e32 v11, v169
	v_lshl_add_u64 v[10:11], v[4:5], 0, v[10:11]
	v_lshl_add_u64 v[10:11], v[10:11], 0, v[168:169]
	global_load_dwordx2 v[10:11], v[10:11], off
	s_waitcnt vmcnt(0)
	v_lshlrev_b32_e32 v13, 16, v10
	v_and_b32_e32 v10, 0xffff0000, v10
	v_mul_f32_e32 v10, v1, v10
	v_fmac_f32_e32 v10, v0, v13
	v_lshlrev_b32_e32 v13, 16, v11
	v_fmac_f32_e32 v10, v2, v13
	v_and_b32_e32 v11, 0xffff0000, v11
	v_fmac_f32_e32 v10, v3, v11
	s_nop 1
	v_add_f32_dpp v10, v10, v10 quad_perm:[1,0,3,2] row_mask:0xf bank_mask:0xf bound_ctrl:1
	s_nop 1
	v_add_f32_dpp v10, v10, v10 quad_perm:[2,3,0,1] row_mask:0xf bank_mask:0xf bound_ctrl:1
	s_nop 1
	v_add_f32_dpp v10, v10, v10 row_half_mirror row_mask:0xf bank_mask:0xf bound_ctrl:1
	s_nop 1
	v_add_f32_dpp v10, v10, v10 row_mirror row_mask:0xf bank_mask:0xf bound_ctrl:1
	s_nop 0
	v_readlane_b32 s18, v10, 0
	v_readlane_b32 s11, v10, 16
	v_readlane_b32 s19, v10, 32
	v_readlane_b32 s20, v10, 48
	s_and_saveexec_b64 s[6:7], vcc
	v_mov_b32_e32 v10, s11
	v_mov_b32_e32 v11, s20
	v_pk_add_f32 v[10:11], s[18:19], v[10:11]
	s_nop 0
	v_add_f32_e32 v10, v10, v11
	ds_write_b32 v9, v10 offset:10504
	s_or_b64 exec, exec, s[6:7]
	v_or_b32_e32 v10, 3, v6
	v_and_or_b32 v10, v10, 11, v7
	v_lshlrev_b32_e32 v10, 4, v10
	v_mov_b32_e32 v11, v169
	v_lshl_add_u64 v[10:11], v[4:5], 0, v[10:11]
	v_lshl_add_u64 v[10:11], v[10:11], 0, v[168:169]
	global_load_dwordx2 v[10:11], v[10:11], off
	s_waitcnt vmcnt(0)
	v_lshlrev_b32_e32 v13, 16, v10
	v_and_b32_e32 v10, 0xffff0000, v10
	v_mul_f32_e32 v10, v1, v10
	v_fmac_f32_e32 v10, v0, v13
	v_lshlrev_b32_e32 v13, 16, v11
	v_fmac_f32_e32 v10, v2, v13
	v_and_b32_e32 v11, 0xffff0000, v11
	v_fmac_f32_e32 v10, v3, v11
	s_nop 1
	v_add_f32_dpp v10, v10, v10 quad_perm:[1,0,3,2] row_mask:0xf bank_mask:0xf bound_ctrl:1
	s_nop 1
	v_add_f32_dpp v10, v10, v10 quad_perm:[2,3,0,1] row_mask:0xf bank_mask:0xf bound_ctrl:1
	s_nop 1
	v_add_f32_dpp v10, v10, v10 row_half_mirror row_mask:0xf bank_mask:0xf bound_ctrl:1
	s_nop 1
	v_add_f32_dpp v10, v10, v10 row_mirror row_mask:0xf bank_mask:0xf bound_ctrl:1
	s_nop 0
	v_readlane_b32 s18, v10, 0
	v_readlane_b32 s11, v10, 16
	v_readlane_b32 s19, v10, 32
	v_readlane_b32 s20, v10, 48
	s_and_saveexec_b64 s[6:7], vcc
	v_mov_b32_e32 v10, s11
	v_mov_b32_e32 v11, s20
	v_pk_add_f32 v[10:11], s[18:19], v[10:11]
	s_nop 0
	v_add_f32_e32 v10, v10, v11
	ds_write_b32 v9, v10 offset:10508
	s_or_b64 exec, exec, s[6:7]
	v_or_b32_e32 v10, 4, v6
	v_and_or_b32 v10, v10, 12, v7
	v_lshlrev_b32_e32 v10, 4, v10
	v_mov_b32_e32 v11, v169
	v_lshl_add_u64 v[10:11], v[4:5], 0, v[10:11]
	v_lshl_add_u64 v[10:11], v[10:11], 0, v[168:169]
	global_load_dwordx2 v[10:11], v[10:11], off
	s_waitcnt vmcnt(0)
	v_lshlrev_b32_e32 v13, 16, v10
	v_and_b32_e32 v10, 0xffff0000, v10
	v_mul_f32_e32 v10, v1, v10
	v_fmac_f32_e32 v10, v0, v13
	v_lshlrev_b32_e32 v13, 16, v11
	v_fmac_f32_e32 v10, v2, v13
	v_and_b32_e32 v11, 0xffff0000, v11
	v_fmac_f32_e32 v10, v3, v11
	s_nop 1
	v_add_f32_dpp v10, v10, v10 quad_perm:[1,0,3,2] row_mask:0xf bank_mask:0xf bound_ctrl:1
	s_nop 1
	v_add_f32_dpp v10, v10, v10 quad_perm:[2,3,0,1] row_mask:0xf bank_mask:0xf bound_ctrl:1
	s_nop 1
	v_add_f32_dpp v10, v10, v10 row_half_mirror row_mask:0xf bank_mask:0xf bound_ctrl:1
	s_nop 1
	v_add_f32_dpp v10, v10, v10 row_mirror row_mask:0xf bank_mask:0xf bound_ctrl:1
	s_nop 0
	v_readlane_b32 s18, v10, 0
	v_readlane_b32 s11, v10, 16
	v_readlane_b32 s19, v10, 32
	v_readlane_b32 s20, v10, 48
	s_and_saveexec_b64 s[6:7], vcc
	v_mov_b32_e32 v10, s11
	v_mov_b32_e32 v11, s20
	v_pk_add_f32 v[10:11], s[18:19], v[10:11]
	s_nop 0
	v_add_f32_e32 v10, v10, v11
	ds_write_b32 v9, v10 offset:10512
	s_or_b64 exec, exec, s[6:7]
	v_or_b32_e32 v10, 5, v6
	v_and_or_b32 v10, v10, 13, v7
	v_lshlrev_b32_e32 v10, 4, v10
	v_mov_b32_e32 v11, v169
	v_lshl_add_u64 v[10:11], v[4:5], 0, v[10:11]
	v_lshl_add_u64 v[10:11], v[10:11], 0, v[168:169]
	global_load_dwordx2 v[10:11], v[10:11], off
	s_waitcnt vmcnt(0)
	v_lshlrev_b32_e32 v13, 16, v10
	v_and_b32_e32 v10, 0xffff0000, v10
	v_mul_f32_e32 v10, v1, v10
	v_fmac_f32_e32 v10, v0, v13
	v_lshlrev_b32_e32 v13, 16, v11
	v_fmac_f32_e32 v10, v2, v13
	v_and_b32_e32 v11, 0xffff0000, v11
	v_fmac_f32_e32 v10, v3, v11
	s_nop 1
	v_add_f32_dpp v10, v10, v10 quad_perm:[1,0,3,2] row_mask:0xf bank_mask:0xf bound_ctrl:1
	s_nop 1
	v_add_f32_dpp v10, v10, v10 quad_perm:[2,3,0,1] row_mask:0xf bank_mask:0xf bound_ctrl:1
	s_nop 1
	v_add_f32_dpp v10, v10, v10 row_half_mirror row_mask:0xf bank_mask:0xf bound_ctrl:1
	s_nop 1
	v_add_f32_dpp v10, v10, v10 row_mirror row_mask:0xf bank_mask:0xf bound_ctrl:1
	s_nop 0
	v_readlane_b32 s18, v10, 0
	v_readlane_b32 s11, v10, 16
	v_readlane_b32 s19, v10, 32
	v_readlane_b32 s20, v10, 48
	s_and_saveexec_b64 s[6:7], vcc
	v_mov_b32_e32 v10, s11
	v_mov_b32_e32 v11, s20
	v_pk_add_f32 v[10:11], s[18:19], v[10:11]
	s_nop 0
	v_add_f32_e32 v10, v10, v11
	ds_write_b32 v9, v10 offset:10516
	s_or_b64 exec, exec, s[6:7]
	v_or_b32_e32 v10, 6, v6
	v_and_or_b32 v10, v10, 14, v7
	v_lshlrev_b32_e32 v10, 4, v10
	v_mov_b32_e32 v11, v169
	v_lshl_add_u64 v[10:11], v[4:5], 0, v[10:11]
	v_lshl_add_u64 v[10:11], v[10:11], 0, v[168:169]
	global_load_dwordx2 v[10:11], v[10:11], off
	s_waitcnt vmcnt(0)
	v_lshlrev_b32_e32 v13, 16, v10
	v_and_b32_e32 v10, 0xffff0000, v10
	v_mul_f32_e32 v10, v1, v10
	v_fmac_f32_e32 v10, v0, v13
	v_lshlrev_b32_e32 v13, 16, v11
	v_fmac_f32_e32 v10, v2, v13
	v_and_b32_e32 v11, 0xffff0000, v11
	v_fmac_f32_e32 v10, v3, v11
	s_nop 1
	v_add_f32_dpp v10, v10, v10 quad_perm:[1,0,3,2] row_mask:0xf bank_mask:0xf bound_ctrl:1
	s_nop 1
	v_add_f32_dpp v10, v10, v10 quad_perm:[2,3,0,1] row_mask:0xf bank_mask:0xf bound_ctrl:1
	s_nop 1
	v_add_f32_dpp v10, v10, v10 row_half_mirror row_mask:0xf bank_mask:0xf bound_ctrl:1
	s_nop 1
	v_add_f32_dpp v10, v10, v10 row_mirror row_mask:0xf bank_mask:0xf bound_ctrl:1
	s_nop 0
	v_readlane_b32 s18, v10, 0
	v_readlane_b32 s11, v10, 16
	v_readlane_b32 s19, v10, 32
	v_readlane_b32 s20, v10, 48
	s_and_saveexec_b64 s[6:7], vcc
	v_mov_b32_e32 v10, s11
	v_mov_b32_e32 v11, s20
	v_pk_add_f32 v[10:11], s[18:19], v[10:11]
	s_nop 0
	v_add_f32_e32 v10, v10, v11
	ds_write_b32 v9, v10 offset:10520
	s_or_b64 exec, exec, s[6:7]
	v_or_b32_e32 v6, 7, v6
	v_and_or_b32 v6, v6, 15, v7
	v_lshlrev_b32_e32 v6, 4, v6
	v_mov_b32_e32 v7, v169
	v_lshl_add_u64 v[4:5], v[4:5], 0, v[6:7]
	v_lshl_add_u64 v[4:5], v[4:5], 0, v[168:169]
	global_load_dwordx2 v[4:5], v[4:5], off
	s_waitcnt vmcnt(0)
	v_lshlrev_b32_e32 v6, 16, v4
	v_and_b32_e32 v4, 0xffff0000, v4
	v_mul_f32_e32 v1, v1, v4
	v_lshlrev_b32_e32 v7, 16, v5
	v_fmac_f32_e32 v1, v0, v6
	v_and_b32_e32 v5, 0xffff0000, v5
	v_fmac_f32_e32 v1, v2, v7
	v_fmac_f32_e32 v1, v3, v5
	s_nop 1
	v_add_f32_dpp v0, v1, v1 quad_perm:[1,0,3,2] row_mask:0xf bank_mask:0xf bound_ctrl:1
	s_nop 1
	v_add_f32_dpp v0, v0, v0 quad_perm:[2,3,0,1] row_mask:0xf bank_mask:0xf bound_ctrl:1
	s_nop 1
	v_add_f32_dpp v0, v0, v0 row_half_mirror row_mask:0xf bank_mask:0xf bound_ctrl:1
	s_nop 1
	v_add_f32_dpp v0, v0, v0 row_mirror row_mask:0xf bank_mask:0xf bound_ctrl:1
	s_nop 0
	v_readlane_b32 s18, v0, 0
	v_readlane_b32 s11, v0, 16
	v_readlane_b32 s19, v0, 32
	v_readlane_b32 s20, v0, 48
	s_and_saveexec_b64 s[6:7], vcc
	v_mov_b32_e32 v0, s11
	v_mov_b32_e32 v1, s20
	v_pk_add_f32 v[0:1], s[18:19], v[0:1]
	s_nop 0
	v_add_f32_e32 v0, v0, v1
	ds_write_b32 v9, v0 offset:10524
	s_or_b64 exec, exec, s[6:7]
	v_lshlrev_b32_e32 v2, 1, v12
	v_lshlrev_b32_e32 v1, 8, v33
	v_and_b32_e32 v2, 32, v2
	s_add_u32 s4, s4, s16
	v_or3_b32 v1, v2, v1, v63
	s_addc_u32 s5, s5, s17
	v_and_b32_e32 v7, 0x200, v8
	v_lshlrev_b32_e32 v50, 3, v1
	s_add_u32 s4, s4, 0x2c240000
	v_or_b32_e32 v30, v50, v7
	v_or_b32_e32 v56, 0x80, v50
	s_addc_u32 s5, s5, 0
	v_ashrrev_i32_e32 v31, 31, v30
	v_or_b32_e32 v54, v56, v7
	v_mov_b32_e32 v0, v169
	v_mov_b32_e32 v4, v169
	v_mov_b32_e32 v10, v169
	v_mov_b32_e32 v14, v169
	v_lshl_add_u64 v[2:3], v[30:31], 1, s[4:5]
	v_ashrrev_i32_e32 v55, 31, v54
	global_load_dwordx4 v[18:21], v[2:3], off
	v_lshl_add_u64 v[2:3], v[54:55], 1, s[4:5]
	global_load_dwordx4 v[22:25], v[2:3], off
	v_and_b32_e32 v5, 48, v32
	v_mul_u32_u24_e32 v6, 0x90, v63
	v_add3_u32 v58, 0, v5, v6
	ds_read_b128 v[6:9], v58
	ds_read_b128 v[34:37], v58 offset:2304
	v_mov_b32_e32 v1, v0
	v_mov_b32_e32 v2, v0
	v_mov_b32_e32 v3, v0
	v_mov_b32_e32 v5, v4
	v_mov_b32_e32 v11, v10
	v_mov_b32_e32 v12, v10
	v_mov_b32_e32 v13, v10
	v_ashrrev_i32_e32 v31, 31, v50
	v_ashrrev_i32_e32 v55, 31, v56
	v_mov_b32_e32 v15, v14
	v_mov_b32_e32 v16, v14
	v_mov_b32_e32 v17, v14
	s_lshl_b32 s6, s2, 8
	s_ashr_i32 s7, s6, 31
	v_mov_b32_e32 v59, v169
	v_and_b32_e32 v32, 0x3fffffc0, v32
	v_lshl_add_u32 v62, v66, 2, 0
	v_cmp_eq_u32_e32 vcc, 0, v63
	s_waitcnt vmcnt(1) lgkmcnt(1)
	v_mfma_f32_16x16x32_bf16 v[26:29], v[6:9], v[18:21], v[0:3]
	s_waitcnt vmcnt(0)
	v_mfma_f32_16x16x32_bf16 v[0:3], v[6:9], v[22:25], v[0:3]
	v_mov_b32_e32 v6, v4
	v_mov_b32_e32 v7, v4
	s_waitcnt lgkmcnt(0)
	s_nop 0
	v_mfma_f32_16x16x32_bf16 v[38:41], v[34:37], v[18:21], v[4:7]
	v_mfma_f32_16x16x32_bf16 v[4:7], v[34:37], v[22:25], v[4:7]
	ds_read_b128 v[34:37], v58 offset:4608
	s_waitcnt lgkmcnt(0)
	v_mfma_f32_16x16x32_bf16 v[42:45], v[34:37], v[18:21], v[10:13]
	v_mfma_f32_16x16x32_bf16 v[8:11], v[34:37], v[22:25], v[10:13]
	ds_read_b128 v[34:37], v58 offset:6912
	s_nop 1
	v_lshl_add_u64 v[12:13], v[30:31], 1, s[4:5]
	global_load_dwordx4 v[50:53], v[12:13], off offset:2048
	v_lshl_add_u64 v[12:13], v[54:55], 1, s[4:5]
	global_load_dwordx4 v[54:57], v[12:13], off offset:2048
	s_waitcnt lgkmcnt(0)
	v_mfma_f32_16x16x32_bf16 v[46:49], v[34:37], v[18:21], v[14:17]
	s_lshl_b64 s[4:5], s[6:7], 2
	s_add_u32 s14, s14, s4
	s_addc_u32 s15, s15, s5
	v_mfma_f32_16x16x32_bf16 v[34:37], v[34:37], v[22:25], v[14:17]
	s_nop 2
	ds_read_b128 v[12:15], v58 offset:64
	s_waitcnt vmcnt(1) lgkmcnt(0)
	v_mfma_f32_16x16x32_bf16 v[28:31], v[12:15], v[50:53], v[26:29]
	s_waitcnt vmcnt(0)
	v_mfma_f32_16x16x32_bf16 v[24:27], v[12:15], v[54:57], v[0:3]
	s_nop 2
	ds_read_b128 v[0:3], v58 offset:2368
	s_waitcnt lgkmcnt(0)
	v_mfma_f32_16x16x32_bf16 v[20:23], v[0:3], v[50:53], v[38:41]
	s_nop 2
	v_lshl_add_u32 v40, v32, 2, 0
	v_mov_b32_e32 v39, v169
	v_mfma_f32_16x16x32_bf16 v[16:19], v[0:3], v[54:57], v[4:7]
	ds_read_b128 v[0:3], v58 offset:4672
	s_nop 1
	ds_read_b128 v[4:7], v58 offset:6976
	s_waitcnt lgkmcnt(1)
	v_mfma_f32_16x16x32_bf16 v[12:15], v[0:3], v[50:53], v[42:45]
	v_lshlrev_b32_e32 v58, 2, v63
	s_waitcnt lgkmcnt(0)
	s_barrier
	v_mfma_f32_16x16x32_bf16 v[8:11], v[0:3], v[54:57], v[8:11]
	v_mfma_f32_16x16x32_bf16 v[0:3], v[4:7], v[50:53], v[46:49]
	v_mfma_f32_16x16x32_bf16 v[4:7], v[4:7], v[54:57], v[34:37]
	s_nop 2
	v_lshlrev_b32_e32 v36, 5, v33
	v_ashrrev_i32_e32 v37, 31, v36
	v_lshl_add_u64 v[34:35], v[36:37], 2, s[14:15]
	v_lshl_add_u64 v[34:35], v[34:35], 0, v[58:59]
	s_mov_b64 s[14:15], 0x9640000
	v_lshl_add_u64 v[60:61], v[34:35], 0, s[14:15]
	v_or_b32_e32 v210, s24, v66
	v_lshlrev_b32_e32 v208, 12, v210
	v_mov_b32_e32 v209, v169
	s_mov_b64 s[26:27], 0x1000
	v_lshl_add_u64 v[208:209], v[60:61], 0, v[208:209]
	global_load_dword v176, v[208:209], off
	global_load_dword v177, v[208:209], off offset:64
	v_lshl_add_u64 v[210:211], v[208:209], 0, s[26:27]
	global_load_dword v178, v[210:211], off
	global_load_dword v179, v[210:211], off offset:64
	v_lshl_add_u64 v[210:211], v[210:211], 0, s[26:27]
	global_load_dword v180, v[210:211], off
	global_load_dword v181, v[210:211], off offset:64
	v_lshl_add_u64 v[210:211], v[210:211], 0, s[26:27]
	global_load_dword v182, v[210:211], off
	global_load_dword v183, v[210:211], off offset:64
	s_mov_b64 s[26:27], 0x10000
	v_lshl_add_u64 v[208:209], v[208:209], 0, s[26:27]
	s_mov_b64 s[26:27], 0x1000
	global_load_dword v184, v[208:209], off
	global_load_dword v185, v[208:209], off offset:64
	v_lshl_add_u64 v[210:211], v[208:209], 0, s[26:27]
	global_load_dword v186, v[210:211], off
	global_load_dword v187, v[210:211], off offset:64
	v_lshl_add_u64 v[210:211], v[210:211], 0, s[26:27]
	global_load_dword v188, v[210:211], off
	global_load_dword v189, v[210:211], off offset:64
	v_lshl_add_u64 v[210:211], v[210:211], 0, s[26:27]
	global_load_dword v190, v[210:211], off
	global_load_dword v191, v[210:211], off offset:64
	s_mov_b64 s[26:27], 0x10000
	v_lshl_add_u64 v[208:209], v[208:209], 0, s[26:27]
	s_mov_b64 s[26:27], 0x1000
	global_load_dword v192, v[208:209], off
	global_load_dword v193, v[208:209], off offset:64
	v_lshl_add_u64 v[210:211], v[208:209], 0, s[26:27]
	global_load_dword v194, v[210:211], off
	global_load_dword v195, v[210:211], off offset:64
	v_lshl_add_u64 v[210:211], v[210:211], 0, s[26:27]
	global_load_dword v196, v[210:211], off
	global_load_dword v197, v[210:211], off offset:64
	v_lshl_add_u64 v[210:211], v[210:211], 0, s[26:27]
	global_load_dword v198, v[210:211], off
	global_load_dword v199, v[210:211], off offset:64
	s_mov_b64 s[26:27], 0x10000
	v_lshl_add_u64 v[208:209], v[208:209], 0, s[26:27]
	s_mov_b64 s[26:27], 0x1000
	global_load_dword v200, v[208:209], off
	global_load_dword v201, v[208:209], off offset:64
	v_lshl_add_u64 v[210:211], v[208:209], 0, s[26:27]
	global_load_dword v202, v[210:211], off
	global_load_dword v203, v[210:211], off offset:64
	v_lshl_add_u64 v[210:211], v[210:211], 0, s[26:27]
	global_load_dword v204, v[210:211], off
	global_load_dword v205, v[210:211], off offset:64
	v_lshl_add_u64 v[210:211], v[210:211], 0, s[26:27]
	global_load_dword v206, v[210:211], off
	global_load_dword v207, v[210:211], off offset:64
	ds_read2st64_b32 v[32:33], v62 offset0:38 offset1:39
	ds_read2st64_b32 v[34:35], v62 offset0:40 offset1:41
	v_or_b32_e32 v59, s24, v66
	v_lshlrev_b32_e32 v38, 12, v59
	s_waitcnt lgkmcnt(1)
	v_mul_f32_e32 v32, 0xbfb8aa3b, v32
	v_exp_f32_e32 v32, v32
	s_waitcnt lgkmcnt(0)
	v_fmac_f32_e32 v34, v33, v35
	v_max_f32_e64 v32, |v34|, v32
	v_lshl_add_u64 v[34:35], v[60:61], 0, v[38:39]
	s_waitcnt vmcnt(0)
	v_mov_b32_e32 v39, v176
	v_rcp_f32_e32 v32, v32
	s_waitcnt vmcnt(0)
	v_fma_f32 v28, v33, v39, v28
	v_mul_f32_e32 v88, v28, v32
	v_mov_b32_e32 v28, v177
	v_lshl_add_u32 v39, v66, 2, v40
	s_waitcnt vmcnt(0)
	v_fma_f32 v24, v33, v28, v24
	v_mul_f32_e32 v90, v24, v32
	v_mul_f32_e32 v24, v90, v90
	v_fmac_f32_e32 v24, v88, v88
	s_nop 1
	v_add_f32_dpp v24, v24, v24 quad_perm:[1,0,3,2] row_mask:0xf bank_mask:0xf bound_ctrl:1
	s_nop 1
	v_add_f32_dpp v24, v24, v24 quad_perm:[2,3,0,1] row_mask:0xf bank_mask:0xf bound_ctrl:1
	s_nop 1
	v_add_f32_dpp v24, v24, v24 row_half_mirror row_mask:0xf bank_mask:0xf bound_ctrl:1
	s_nop 1
	v_mov_b32_dpp v28, v24 row_mirror row_mask:0xf bank_mask:0xf bound_ctrl:1
	s_and_saveexec_b64 s[14:15], vcc
	v_add_f32_e32 v24, v24, v28
	ds_write_b32 v39, v24 offset:10752
	s_or_b64 exec, exec, s[14:15]
	v_add_u32_e32 v24, 4, v62
	ds_read2st64_b32 v[32:33], v24 offset0:38 offset1:39
	ds_read2st64_b32 v[34:35], v24 offset0:40 offset1:41
	v_or3_b32 v28, v66, s24, 1
	v_lshlrev_b32_e32 v56, 12, v28
	v_mov_b32_e32 v57, v169
	s_waitcnt lgkmcnt(1)
	v_mul_f32_e32 v24, 0xbfb8aa3b, v32
	v_exp_f32_e32 v24, v24
	s_waitcnt lgkmcnt(0)
	v_fmac_f32_e32 v34, v33, v35
	v_max_f32_e64 v24, |v34|, v24
	v_lshl_add_u64 v[34:35], v[60:61], 0, v[56:57]
	v_mov_b32_e32 v28, v178
	v_rcp_f32_e32 v24, v24
	s_waitcnt vmcnt(0)
	v_fma_f32 v28, v33, v28, v29
	v_mul_f32_e32 v89, v28, v24
	v_mov_b32_e32 v28, v179
	s_waitcnt vmcnt(0)
	v_fma_f32 v25, v33, v28, v25
	v_mul_f32_e32 v91, v25, v24
	v_mul_f32_e32 v24, v91, v91
	v_fmac_f32_e32 v24, v89, v89
	s_nop 1
	v_add_f32_dpp v24, v24, v24 quad_perm:[1,0,3,2] row_mask:0xf bank_mask:0xf bound_ctrl:1
	s_nop 1
	v_add_f32_dpp v24, v24, v24 quad_perm:[2,3,0,1] row_mask:0xf bank_mask:0xf bound_ctrl:1
	s_nop 1
	v_add_f32_dpp v24, v24, v24 row_half_mirror row_mask:0xf bank_mask:0xf bound_ctrl:1
	s_nop 1
	v_mov_b32_dpp v25, v24 row_mirror row_mask:0xf bank_mask:0xf bound_ctrl:1
	s_and_saveexec_b64 s[14:15], vcc
	v_add_f32_e32 v24, v24, v25
	ds_write_b32 v39, v24 offset:10756
	s_or_b64 exec, exec, s[14:15]
	v_add_u32_e32 v24, 8, v62
	ds_read2st64_b32 v[28:29], v24 offset0:38 offset1:39
	ds_read2st64_b32 v[24:25], v24 offset0:40 offset1:41
	s_waitcnt lgkmcnt(0)
	v_fmac_f32_e32 v24, v29, v25
	v_mul_f32_e32 v25, 0xbfb8aa3b, v28
	v_exp_f32_e32 v25, v25
	s_nop 0
	v_max_f32_e64 v24, |v24|, v25
	v_rcp_f32_e32 v28, v24
	v_or3_b32 v24, v66, s24, 2
	v_lshlrev_b32_e32 v24, 12, v24
	v_mov_b32_e32 v25, v169
	v_lshl_add_u64 v[32:33], v[60:61], 0, v[24:25]
	v_mov_b32_e32 v25, v180
	s_waitcnt vmcnt(0)
	v_fma_f32 v25, v29, v25, v30
	v_mul_f32_e32 v30, v25, v28
	v_mov_b32_e32 v25, v181
	s_waitcnt vmcnt(0)
	v_fma_f32 v25, v29, v25, v26
	v_mul_f32_e32 v92, v25, v28
	v_mul_f32_e32 v25, v92, v92
	v_fmac_f32_e32 v25, v30, v30
	s_nop 1
	v_add_f32_dpp v25, v25, v25 quad_perm:[1,0,3,2] row_mask:0xf bank_mask:0xf bound_ctrl:1
	s_nop 1
	v_add_f32_dpp v25, v25, v25 quad_perm:[2,3,0,1] row_mask:0xf bank_mask:0xf bound_ctrl:1
	s_nop 1
	v_add_f32_dpp v25, v25, v25 row_half_mirror row_mask:0xf bank_mask:0xf bound_ctrl:1
	s_nop 1
	v_mov_b32_dpp v26, v25 row_mirror row_mask:0xf bank_mask:0xf bound_ctrl:1
	s_and_saveexec_b64 s[14:15], vcc
	v_add_f32_e32 v25, v25, v26
	ds_write_b32 v39, v25 offset:10760
	s_or_b64 exec, exec, s[14:15]
	v_add_u32_e32 v25, 12, v62
	ds_read2st64_b32 v[32:33], v25 offset0:38 offset1:39
	ds_read2st64_b32 v[28:29], v25 offset0:40 offset1:41
	v_or3_b32 v26, v66, s24, 3
	s_waitcnt lgkmcnt(1)
	v_mul_f32_e32 v25, 0xbfb8aa3b, v32
	v_exp_f32_e32 v25, v25
	s_waitcnt lgkmcnt(0)
	v_fmac_f32_e32 v28, v33, v29
	v_mov_b32_e32 v29, v169
	v_max_f32_e64 v25, |v28|, v25
	v_lshlrev_b32_e32 v28, 12, v26
	v_lshl_add_u64 v[34:35], v[60:61], 0, v[28:29]
	v_mov_b32_e32 v26, v182
	v_rcp_f32_e32 v25, v25
	s_waitcnt vmcnt(0)
	v_fmac_f32_e32 v31, v33, v26
	v_mov_b32_e32 v26, v183
	v_mul_f32_e32 v31, v31, v25
	s_waitcnt vmcnt(0)
	v_fmac_f32_e32 v27, v33, v26
	v_mul_f32_e32 v93, v27, v25
	v_mul_f32_e32 v25, v93, v93
	v_fmac_f32_e32 v25, v31, v31
	s_nop 1
	v_add_f32_dpp v25, v25, v25 quad_perm:[1,0,3,2] row_mask:0xf bank_mask:0xf bound_ctrl:1
	s_nop 1
	v_add_f32_dpp v25, v25, v25 quad_perm:[2,3,0,1] row_mask:0xf bank_mask:0xf bound_ctrl:1
	s_nop 1
	v_add_f32_dpp v25, v25, v25 row_half_mirror row_mask:0xf bank_mask:0xf bound_ctrl:1
	s_nop 1
	v_mov_b32_dpp v26, v25 row_mirror row_mask:0xf bank_mask:0xf bound_ctrl:1
	s_and_saveexec_b64 s[14:15], vcc
	v_add_f32_e32 v25, v25, v26
	ds_write_b32 v39, v25 offset:10764
	s_or_b64 exec, exec, s[14:15]
	v_add_u32_e32 v25, 64, v62
	ds_read2st64_b32 v[32:33], v25 offset0:38 offset1:39
	ds_read2st64_b32 v[26:27], v25 offset0:40 offset1:41
	s_waitcnt lgkmcnt(1)
	v_mul_f32_e32 v25, 0xbfb8aa3b, v32
	v_exp_f32_e32 v25, v25
	s_waitcnt lgkmcnt(0)
	v_fmac_f32_e32 v26, v33, v27
	v_mov_b32_e32 v27, v169
	v_max_f32_e64 v25, |v26|, v25
	v_or3_b32 v26, v66, s24, 16
	v_lshlrev_b32_e32 v26, 12, v26
	v_lshl_add_u64 v[34:35], v[60:61], 0, v[26:27]
	v_mov_b32_e32 v27, v184
	v_rcp_f32_e32 v25, v25
	s_waitcnt vmcnt(0)
	v_fma_f32 v20, v33, v27, v20
	v_mov_b32_e32 v27, v185
	v_mul_f32_e32 v20, v20, v25
	s_waitcnt vmcnt(0)
	v_fma_f32 v16, v33, v27, v16
	v_mul_f32_e32 v16, v16, v25
	v_mul_f32_e32 v25, v16, v16
	v_fmac_f32_e32 v25, v20, v20
	s_nop 1
	v_add_f32_dpp v25, v25, v25 quad_perm:[1,0,3,2] row_mask:0xf bank_mask:0xf bound_ctrl:1
	s_nop 1
	v_add_f32_dpp v25, v25, v25 quad_perm:[2,3,0,1] row_mask:0xf bank_mask:0xf bound_ctrl:1
	s_nop 1
	v_add_f32_dpp v25, v25, v25 row_half_mirror row_mask:0xf bank_mask:0xf bound_ctrl:1
	s_nop 1
	v_mov_b32_dpp v27, v25 row_mirror row_mask:0xf bank_mask:0xf bound_ctrl:1
	s_and_saveexec_b64 s[14:15], vcc
	v_add_f32_e32 v25, v25, v27
	ds_write_b32 v39, v25 offset:10816
	s_or_b64 exec, exec, s[14:15]
	v_add_u32_e32 v25, 0x44, v62
	ds_read2st64_b32 v[32:33], v25 offset0:38 offset1:39
	ds_read2st64_b32 v[34:35], v25 offset0:40 offset1:41
	v_or3_b32 v27, v66, s24, 17
	v_lshlrev_b32_e32 v40, 12, v27
	v_mov_b32_e32 v41, v169
	s_waitcnt lgkmcnt(1)
	v_mul_f32_e32 v25, 0xbfb8aa3b, v32
	v_exp_f32_e32 v25, v25
	s_waitcnt lgkmcnt(0)
	v_fmac_f32_e32 v34, v33, v35
	v_max_f32_e64 v25, |v34|, v25
	v_lshl_add_u64 v[34:35], v[60:61], 0, v[40:41]
	v_mov_b32_e32 v27, v186
	v_rcp_f32_e32 v25, v25
	s_waitcnt vmcnt(0)
	v_fma_f32 v21, v33, v27, v21
	v_mul_f32_e32 v73, v21, v25
	v_mov_b32_e32 v21, v187
	s_waitcnt vmcnt(0)
	v_fma_f32 v17, v33, v21, v17
	v_mul_f32_e32 v72, v17, v25
	v_mul_f32_e32 v17, v72, v72
	v_fmac_f32_e32 v17, v73, v73
	s_nop 1
	v_add_f32_dpp v17, v17, v17 quad_perm:[1,0,3,2] row_mask:0xf bank_mask:0xf bound_ctrl:1
	s_nop 1
	v_add_f32_dpp v17, v17, v17 quad_perm:[2,3,0,1] row_mask:0xf bank_mask:0xf bound_ctrl:1
	s_nop 1
	v_add_f32_dpp v17, v17, v17 row_half_mirror row_mask:0xf bank_mask:0xf bound_ctrl:1
	s_nop 1
	v_mov_b32_dpp v21, v17 row_mirror row_mask:0xf bank_mask:0xf bound_ctrl:1
	s_and_saveexec_b64 s[14:15], vcc
	v_add_f32_e32 v17, v17, v21
	ds_write_b32 v39, v17 offset:10820
	s_or_b64 exec, exec, s[14:15]
	v_add_u32_e32 v17, 0x48, v62
	ds_read2st64_b32 v[32:33], v17 offset0:38 offset1:39
	ds_read2st64_b32 v[34:35], v17 offset0:40 offset1:41
	v_or3_b32 v21, v66, s24, 18
	v_lshlrev_b32_e32 v42, 12, v21
	v_mov_b32_e32 v43, v169
	s_waitcnt lgkmcnt(1)
	v_mul_f32_e32 v17, 0xbfb8aa3b, v32
	v_exp_f32_e32 v17, v17
	s_waitcnt lgkmcnt(0)
	v_fmac_f32_e32 v34, v33, v35
	v_max_f32_e64 v17, |v34|, v17
	v_lshl_add_u64 v[34:35], v[60:61], 0, v[42:43]
	v_mov_b32_e32 v21, v188
	v_rcp_f32_e32 v17, v17
	s_waitcnt vmcnt(0)
	v_fma_f32 v21, v33, v21, v22
	v_mul_f32_e32 v76, v21, v17
	v_mov_b32_e32 v21, v189
	s_waitcnt vmcnt(0)
	v_fma_f32 v18, v33, v21, v18
	v_mul_f32_e32 v77, v18, v17
	v_mul_f32_e32 v17, v77, v77
	v_fmac_f32_e32 v17, v76, v76
	s_nop 1
	v_add_f32_dpp v17, v17, v17 quad_perm:[1,0,3,2] row_mask:0xf bank_mask:0xf bound_ctrl:1
	s_nop 1
	v_add_f32_dpp v17, v17, v17 quad_perm:[2,3,0,1] row_mask:0xf bank_mask:0xf bound_ctrl:1
	s_nop 1
	v_add_f32_dpp v17, v17, v17 row_half_mirror row_mask:0xf bank_mask:0xf bound_ctrl:1
	s_nop 1
	v_mov_b32_dpp v18, v17 row_mirror row_mask:0xf bank_mask:0xf bound_ctrl:1
	s_and_saveexec_b64 s[14:15], vcc
	v_add_f32_e32 v17, v17, v18
	ds_write_b32 v39, v17 offset:10824
	s_or_b64 exec, exec, s[14:15]
	v_add_u32_e32 v17, 0x4c, v62
	ds_read2st64_b32 v[32:33], v17 offset0:38 offset1:39
	ds_read2st64_b32 v[34:35], v17 offset0:40 offset1:41
	v_or3_b32 v18, v66, s24, 19
	v_lshlrev_b32_e32 v44, 12, v18
	v_mov_b32_e32 v45, v169
	s_waitcnt lgkmcnt(1)
	v_mul_f32_e32 v17, 0xbfb8aa3b, v32
	v_exp_f32_e32 v17, v17
	s_waitcnt lgkmcnt(0)
	v_fmac_f32_e32 v34, v33, v35
	v_max_f32_e64 v17, |v34|, v17
	v_lshl_add_u64 v[34:35], v[60:61], 0, v[44:45]
	v_mov_b32_e32 v18, v190
	v_rcp_f32_e32 v17, v17
	s_waitcnt vmcnt(0)
	v_fmac_f32_e32 v23, v33, v18
	v_mov_b32_e32 v18, v191
	v_mul_f32_e32 v75, v23, v17
	s_waitcnt vmcnt(0)
	v_fmac_f32_e32 v19, v33, v18
	v_mul_f32_e32 v74, v19, v17
	v_mul_f32_e32 v17, v74, v74
	v_fmac_f32_e32 v17, v75, v75
	s_nop 1
	v_add_f32_dpp v17, v17, v17 quad_perm:[1,0,3,2] row_mask:0xf bank_mask:0xf bound_ctrl:1
	s_nop 1
	v_add_f32_dpp v17, v17, v17 quad_perm:[2,3,0,1] row_mask:0xf bank_mask:0xf bound_ctrl:1
	s_nop 1
	v_add_f32_dpp v17, v17, v17 row_half_mirror row_mask:0xf bank_mask:0xf bound_ctrl:1
	s_nop 1
	v_mov_b32_dpp v18, v17 row_mirror row_mask:0xf bank_mask:0xf bound_ctrl:1
	s_and_saveexec_b64 s[14:15], vcc
	v_add_f32_e32 v17, v17, v18
	ds_write_b32 v39, v17 offset:10828
	s_or_b64 exec, exec, s[14:15]
	v_add_u32_e32 v17, 0x80, v62
	ds_read2st64_b32 v[18:19], v17 offset0:38 offset1:39
	ds_read2st64_b32 v[22:23], v17 offset0:40 offset1:41
	v_mov_b32_e32 v47, v169
	s_waitcnt lgkmcnt(1)
	v_mul_f32_e32 v17, 0xbfb8aa3b, v18
	v_exp_f32_e32 v17, v17
	v_or3_b32 v18, v66, s24, 32
	s_waitcnt lgkmcnt(0)
	v_fmac_f32_e32 v22, v19, v23
	v_lshlrev_b32_e32 v46, 12, v18
	v_max_f32_e64 v17, |v22|, v17
	v_lshl_add_u64 v[22:23], v[60:61], 0, v[46:47]
	v_mov_b32_e32 v18, v192
	v_rcp_f32_e32 v17, v17
	s_waitcnt vmcnt(0)
	v_fma_f32 v12, v19, v18, v12
	v_mul_f32_e32 v78, v12, v17
	v_mov_b32_e32 v12, v193
	s_waitcnt vmcnt(0)
	v_fma_f32 v8, v19, v12, v8
	v_mul_f32_e32 v80, v8, v17
	v_mul_f32_e32 v8, v80, v80
	v_fmac_f32_e32 v8, v78, v78
	s_nop 1
	v_add_f32_dpp v8, v8, v8 quad_perm:[1,0,3,2] row_mask:0xf bank_mask:0xf bound_ctrl:1
	s_nop 1
	v_add_f32_dpp v8, v8, v8 quad_perm:[2,3,0,1] row_mask:0xf bank_mask:0xf bound_ctrl:1
	s_nop 1
	v_add_f32_dpp v8, v8, v8 row_half_mirror row_mask:0xf bank_mask:0xf bound_ctrl:1
	s_nop 1
	v_mov_b32_dpp v12, v8 row_mirror row_mask:0xf bank_mask:0xf bound_ctrl:1
	s_and_saveexec_b64 s[14:15], vcc
	v_add_f32_e32 v8, v8, v12
	ds_write_b32 v39, v8 offset:10880
	s_or_b64 exec, exec, s[14:15]
	v_add_u32_e32 v8, 0x84, v62
	ds_read2st64_b32 v[18:19], v8 offset0:38 offset1:39
	ds_read2st64_b32 v[22:23], v8 offset0:40 offset1:41
	v_or3_b32 v12, v66, s24, 33
	v_lshlrev_b32_e32 v48, 12, v12
	v_mov_b32_e32 v49, v169
	s_waitcnt lgkmcnt(1)
	v_mul_f32_e32 v8, 0xbfb8aa3b, v18
	v_exp_f32_e32 v8, v8
	s_waitcnt lgkmcnt(0)
	v_fmac_f32_e32 v22, v19, v23
	v_max_f32_e64 v8, |v22|, v8
	v_lshl_add_u64 v[22:23], v[60:61], 0, v[48:49]
	v_mov_b32_e32 v12, v194
	v_rcp_f32_e32 v8, v8
	s_waitcnt vmcnt(0)
	v_fma_f32 v12, v19, v12, v13
	v_mul_f32_e32 v79, v12, v8
	v_mov_b32_e32 v12, v195
	s_waitcnt vmcnt(0)
	v_fma_f32 v9, v19, v12, v9
	v_mul_f32_e32 v81, v9, v8
	v_mul_f32_e32 v8, v81, v81
	v_fmac_f32_e32 v8, v79, v79
	s_nop 1
	v_add_f32_dpp v8, v8, v8 quad_perm:[1,0,3,2] row_mask:0xf bank_mask:0xf bound_ctrl:1
	s_nop 1
	v_add_f32_dpp v8, v8, v8 quad_perm:[2,3,0,1] row_mask:0xf bank_mask:0xf bound_ctrl:1
	s_nop 1
	v_add_f32_dpp v8, v8, v8 row_half_mirror row_mask:0xf bank_mask:0xf bound_ctrl:1
	s_nop 1
	v_mov_b32_dpp v9, v8 row_mirror row_mask:0xf bank_mask:0xf bound_ctrl:1
	s_and_saveexec_b64 s[14:15], vcc
	v_add_f32_e32 v8, v8, v9
	ds_write_b32 v39, v8 offset:10884
	s_or_b64 exec, exec, s[14:15]
	v_add_u32_e32 v12, 0x88, v62
	ds_read2st64_b32 v[8:9], v12 offset0:38 offset1:39
	ds_read2st64_b32 v[12:13], v12 offset0:40 offset1:41
	v_mov_b32_e32 v51, v169
	s_waitcnt lgkmcnt(1)
	v_mul_f32_e32 v8, 0xbfb8aa3b, v8
	v_exp_f32_e32 v8, v8
	s_waitcnt lgkmcnt(0)
	v_fmac_f32_e32 v12, v9, v13
	v_max_f32_e64 v8, |v12|, v8
	v_or3_b32 v12, v66, s24, 34
	v_lshlrev_b32_e32 v50, 12, v12
	v_lshl_add_u64 v[12:13], v[60:61], 0, v[50:51]
	v_mov_b32_e32 v17, v196
	v_rcp_f32_e32 v8, v8
	v_mov_b32_e32 v12, v197
	s_waitcnt vmcnt(1)
	v_fma_f32 v14, v9, v17, v14
	v_mul_f32_e32 v82, v14, v8
	s_waitcnt vmcnt(0)
	v_fma_f32 v9, v9, v12, v10
	v_mul_f32_e32 v83, v9, v8
	v_mul_f32_e32 v8, v83, v83
	v_fmac_f32_e32 v8, v82, v82
	s_nop 1
	v_add_f32_dpp v8, v8, v8 quad_perm:[1,0,3,2] row_mask:0xf bank_mask:0xf bound_ctrl:1
	s_nop 1
	v_add_f32_dpp v8, v8, v8 quad_perm:[2,3,0,1] row_mask:0xf bank_mask:0xf bound_ctrl:1
	s_nop 1
	v_add_f32_dpp v8, v8, v8 row_half_mirror row_mask:0xf bank_mask:0xf bound_ctrl:1
	s_nop 1
	v_mov_b32_dpp v9, v8 row_mirror row_mask:0xf bank_mask:0xf bound_ctrl:1
	s_and_saveexec_b64 s[14:15], vcc
	v_add_f32_e32 v8, v8, v9
	ds_write_b32 v39, v8 offset:10888
	s_or_b64 exec, exec, s[14:15]
	v_add_u32_e32 v10, 0x8c, v62
	ds_read2st64_b32 v[8:9], v10 offset0:38 offset1:39
	ds_read2st64_b32 v[12:13], v10 offset0:40 offset1:41
	v_or3_b32 v10, v66, s24, 35
	v_lshlrev_b32_e32 v52, 12, v10
	v_mov_b32_e32 v53, v169
	s_waitcnt lgkmcnt(1)
	v_mul_f32_e32 v8, 0xbfb8aa3b, v8
	v_exp_f32_e32 v8, v8
	s_waitcnt lgkmcnt(0)
	v_fmac_f32_e32 v12, v9, v13
	v_max_f32_e64 v8, |v12|, v8
	v_lshl_add_u64 v[12:13], v[60:61], 0, v[52:53]
	v_mov_b32_e32 v10, v198
	v_rcp_f32_e32 v8, v8
	s_waitcnt vmcnt(0)
	v_fmac_f32_e32 v15, v9, v10
	v_mov_b32_e32 v10, v199
	v_mul_f32_e32 v84, v15, v8
	s_waitcnt vmcnt(0)
	v_fmac_f32_e32 v11, v9, v10
	v_mul_f32_e32 v85, v11, v8
	v_mul_f32_e32 v8, v85, v85
	v_fmac_f32_e32 v8, v84, v84
	s_nop 1
	v_add_f32_dpp v8, v8, v8 quad_perm:[1,0,3,2] row_mask:0xf bank_mask:0xf bound_ctrl:1
	s_nop 1
	v_add_f32_dpp v8, v8, v8 quad_perm:[2,3,0,1] row_mask:0xf bank_mask:0xf bound_ctrl:1
	s_nop 1
	v_add_f32_dpp v8, v8, v8 row_half_mirror row_mask:0xf bank_mask:0xf bound_ctrl:1
	s_nop 1
	v_mov_b32_dpp v9, v8 row_mirror row_mask:0xf bank_mask:0xf bound_ctrl:1
	s_and_saveexec_b64 s[14:15], vcc
	v_add_f32_e32 v8, v8, v9
	ds_write_b32 v39, v8 offset:10892
	s_or_b64 exec, exec, s[14:15]
	v_add_u32_e32 v10, 0xc0, v62
	ds_read2st64_b32 v[8:9], v10 offset0:38 offset1:39
	ds_read2st64_b32 v[10:11], v10 offset0:40 offset1:41
	v_mov_b32_e32 v55, v169
	s_waitcnt lgkmcnt(1)
	v_mul_f32_e32 v8, 0xbfb8aa3b, v8
	v_exp_f32_e32 v8, v8
	s_waitcnt lgkmcnt(0)
	v_fmac_f32_e32 v10, v9, v11
	v_max_f32_e64 v8, |v10|, v8
	v_or3_b32 v10, v66, s24, 48
	v_lshlrev_b32_e32 v54, 12, v10
	v_lshl_add_u64 v[10:11], v[60:61], 0, v[54:55]
	v_mov_b32_e32 v12, v200
	v_rcp_f32_e32 v8, v8
	s_waitcnt vmcnt(0)
	v_fma_f32 v0, v9, v12, v0
	v_mul_f32_e32 v86, v0, v8
	v_mov_b32_e32 v0, v201
	s_waitcnt vmcnt(0)
	v_fma_f32 v0, v9, v0, v4
	v_mul_f32_e32 v87, v0, v8
	v_mul_f32_e32 v0, v87, v87
	v_fmac_f32_e32 v0, v86, v86
	s_nop 1
	v_add_f32_dpp v0, v0, v0 quad_perm:[1,0,3,2] row_mask:0xf bank_mask:0xf bound_ctrl:1
	s_nop 1
	v_add_f32_dpp v0, v0, v0 quad_perm:[2,3,0,1] row_mask:0xf bank_mask:0xf bound_ctrl:1
	s_nop 1
	v_add_f32_dpp v0, v0, v0 row_half_mirror row_mask:0xf bank_mask:0xf bound_ctrl:1
	s_nop 1
	v_mov_b32_dpp v4, v0 row_mirror row_mask:0xf bank_mask:0xf bound_ctrl:1
	s_and_saveexec_b64 s[14:15], vcc
	v_add_f32_e32 v0, v0, v4
	ds_write_b32 v39, v0 offset:10944
	s_or_b64 exec, exec, s[14:15]
	v_add_u32_e32 v0, 0xc4, v62
	ds_read2st64_b32 v[8:9], v0 offset0:38 offset1:39
	ds_read2st64_b32 v[10:11], v0 offset0:40 offset1:41
	v_or3_b32 v4, v66, s24, 49
	v_lshlrev_b32_e32 v32, 12, v4
	v_mov_b32_e32 v33, v169
	s_waitcnt lgkmcnt(1)
	v_mul_f32_e32 v0, 0xbfb8aa3b, v8
	v_exp_f32_e32 v0, v0
	s_waitcnt lgkmcnt(0)
	v_fmac_f32_e32 v10, v9, v11
	v_max_f32_e64 v0, |v10|, v0
	v_lshl_add_u64 v[10:11], v[60:61], 0, v[32:33]
	v_mov_b32_e32 v4, v202
	v_rcp_f32_e32 v0, v0
	s_waitcnt vmcnt(0)
	v_fma_f32 v1, v9, v4, v1
	v_mul_f32_e32 v65, v1, v0
	v_mov_b32_e32 v1, v203
	s_waitcnt vmcnt(0)
	v_fma_f32 v1, v9, v1, v5
	v_mul_f32_e32 v64, v1, v0
	v_mul_f32_e32 v0, v64, v64
	v_fmac_f32_e32 v0, v65, v65
	s_nop 1
	v_add_f32_dpp v0, v0, v0 quad_perm:[1,0,3,2] row_mask:0xf bank_mask:0xf bound_ctrl:1
	s_nop 1
	v_add_f32_dpp v0, v0, v0 quad_perm:[2,3,0,1] row_mask:0xf bank_mask:0xf bound_ctrl:1
	s_nop 1
	v_add_f32_dpp v0, v0, v0 row_half_mirror row_mask:0xf bank_mask:0xf bound_ctrl:1
	s_nop 1
	v_mov_b32_dpp v1, v0 row_mirror row_mask:0xf bank_mask:0xf bound_ctrl:1
	s_and_saveexec_b64 s[14:15], vcc
	v_add_f32_e32 v0, v0, v1
	ds_write_b32 v39, v0 offset:10948
	s_or_b64 exec, exec, s[14:15]
	v_add_u32_e32 v4, 0xc8, v62
	ds_read2st64_b32 v[0:1], v4 offset0:38 offset1:39
	ds_read2st64_b32 v[4:5], v4 offset0:40 offset1:41
	v_mov_b32_e32 v35, v169
	s_waitcnt lgkmcnt(1)
	v_mul_f32_e32 v0, 0xbfb8aa3b, v0
	v_exp_f32_e32 v0, v0
	s_waitcnt lgkmcnt(0)
	v_fmac_f32_e32 v4, v1, v5
	v_max_f32_e64 v0, |v4|, v0
	v_or3_b32 v4, v66, s24, 50
	v_lshlrev_b32_e32 v34, 12, v4
	v_lshl_add_u64 v[4:5], v[60:61], 0, v[34:35]
	v_mov_b32_e32 v8, v204
	v_rcp_f32_e32 v0, v0
	s_waitcnt vmcnt(0)
	v_fma_f32 v2, v1, v8, v2
	v_mul_f32_e32 v67, v2, v0
	v_mov_b32_e32 v2, v205
	s_waitcnt vmcnt(0)
	v_fma_f32 v1, v1, v2, v6
	v_mul_f32_e32 v68, v1, v0
	v_mul_f32_e32 v0, v68, v68
	v_fmac_f32_e32 v0, v67, v67
	s_nop 1
	v_add_f32_dpp v0, v0, v0 quad_perm:[1,0,3,2] row_mask:0xf bank_mask:0xf bound_ctrl:1
	s_nop 1
	v_add_f32_dpp v0, v0, v0 quad_perm:[2,3,0,1] row_mask:0xf bank_mask:0xf bound_ctrl:1
	s_nop 1
	v_add_f32_dpp v0, v0, v0 row_half_mirror row_mask:0xf bank_mask:0xf bound_ctrl:1
	s_nop 1
	v_mov_b32_dpp v1, v0 row_mirror row_mask:0xf bank_mask:0xf bound_ctrl:1
	s_and_saveexec_b64 s[14:15], vcc
	v_add_f32_e32 v0, v0, v1
	ds_write_b32 v39, v0 offset:10952
	s_or_b64 exec, exec, s[14:15]
	v_or3_b32 v0, v66, s24, 51
	v_lshlrev_b32_e32 v168, 12, v0
	v_lshl_add_u64 v[0:1], v[60:61], 0, v[168:169]
	v_mov_b32_e32 v2, v206
	v_mov_b32_e32 v6, v207
	v_add_u32_e32 v4, 0xcc, v62
	ds_read2st64_b32 v[0:1], v4 offset0:38 offset1:39
	ds_read2st64_b32 v[4:5], v4 offset0:40 offset1:41
	s_waitcnt lgkmcnt(1)
	v_mul_f32_e32 v0, 0xbfb8aa3b, v0
	v_exp_f32_e32 v0, v0
	s_waitcnt lgkmcnt(0)
	v_fmac_f32_e32 v4, v1, v5
	v_max_f32_e64 v0, |v4|, v0
	v_rcp_f32_e32 v0, v0
	s_waitcnt vmcnt(1)
	v_fmac_f32_e32 v3, v1, v2
	s_waitcnt vmcnt(0)
	v_fmac_f32_e32 v7, v1, v6
	v_mul_f32_e32 v60, v7, v0
	v_mul_f32_e32 v66, v3, v0
	v_mul_f32_e32 v0, v60, v60
	v_fmac_f32_e32 v0, v66, v66
	s_nop 1
	v_add_f32_dpp v0, v0, v0 quad_perm:[1,0,3,2] row_mask:0xf bank_mask:0xf bound_ctrl:1
	s_nop 1
	v_add_f32_dpp v0, v0, v0 quad_perm:[2,3,0,1] row_mask:0xf bank_mask:0xf bound_ctrl:1
	s_nop 1
	v_add_f32_dpp v0, v0, v0 row_half_mirror row_mask:0xf bank_mask:0xf bound_ctrl:1
	s_nop 1
	v_mov_b32_dpp v1, v0 row_mirror row_mask:0xf bank_mask:0xf bound_ctrl:1
	s_and_saveexec_b64 s[14:15], vcc
	s_cbranch_execz .LBB0_162
	v_add_f32_e32 v0, v0, v1
	ds_write_b32 v39, v0 offset:10956
	s_branch .LBB0_162
